# GQA attention loop first half: row-max, scale and exp of next tile moved from between the barriers into the PV MFMA shadow (16+16+3 spare VGPRs)
# baseline (speedup 1.0000x reference)
; #define SBAR() __builtin_amdgcn_sched_barrier(0)
; __device__ __forceinline__ void finishSM(f32x16& p0, f32x16& p1, float alpha, float& l_reg, bf16x8& pa0, bf16x8& pa1, bf16x8& pa2, bf16x8& pa3) {
; #pragma unroll
;   for (int r = 0; r < 16; ++r) p1[r] = __builtin_amdgcn_exp2f(p1[r]);
;   float ps = 0;
; #pragma unroll
;   for (int r = 0; r < 16; ++r) ps += p0[r];
; #pragma unroll
;   for (int r = 0; r < 16; ++r) ps += p1[r];
;   { auto rr = __builtin_amdgcn_permlane32_swap(__float_as_uint(ps), __float_as_uint(ps), false, false);
;     ps = __uint_as_float(rr[0]) + __uint_as_float(rr[1]); }
;   l_reg = l_reg * alpha + ps;
;     ...
;   PK4(p0, 0, pa0); PK4(p0, 8, pa1); PK4(p1, 0, pa2); PK4(p1, 8, pa3);
;     ...
; }
; template <int DK, int NPARK>
; __device__ __forceinline__ void qkt(f32x16& p0, f32x16& p1, const char* Ks, const bf16x8* qr, const char* qpark, int r32, int hi) {
;   p0 = f32x16{}; p1 = f32x16{};
; #pragma unroll
;   for (int d0 = 0; d0 < DK / 16; ++d0) { const int cb = (d0 * 16 + hi * 8) * 2;
;     bf16x8 b0 = *reinterpret_cast<const bf16x8*>(Ks + kswz<DK>(r32, cb));
;     bf16x8 b1 = *reinterpret_cast<const bf16x8*>(Ks + kswz<DK>(32 + r32, cb));
;     bf16x8 q;
;     if constexpr (NPARK > 0) { if (d0 >= DK / 16 - NPARK) q = *reinterpret_cast<const bf16x8*>(qpark + (d0 - (DK / 16 - NPARK)) * 1024); else q = qr[d0]; } else q = qr[d0];
;     p0 = __builtin_amdgcn_mfma_f32_32x32x16_bf16(b0, q, p0, 0, 0, 0);
;     p1 = __builtin_amdgcn_mfma_f32_32x32x16_bf16(b1, q, p1, 0, 0, 0); }
; }
; template <int DK, int LDQ, int LDK, int LDV, int LDO, int SDEPTH, int NPARK>
; __device__ __forceinline__ void body(const bf16_t* __restrict__ Qb, const bf16_t* __restrict__ Kh, const bf16_t* __restrict__ Vh, bf16_t* __restrict__ Ob, int seq, char* lds, int tid, int wid) {
;     ...
;     SBAR(); qkt<DK, NPARK>(pB0, pB1, K_lds + SHM_K, qr, qpark, r32, hi);
;     finishSM(pA0, pA1, alA, l_reg, pa0, pa1, pa2, pa3); SBAR();
;     SLOAD(SO, (j + SDEPTH) * KVBLK); SBAR();
;     pv_d0(o, vb0, pa0, pa1, pa2, pa3); partialSM<DK>(pB0, pB1, m_reg, mnB, alB);
.LBB0_924:
	ds_read_b128 v[64:67], v161 offset:49152
	ds_read_b128 v[68:71], v161 offset:57344
	ds_read_b128 v[194:197], v170 offset:49152
	ds_read_b128 v[198:201], v170 offset:57344
	v_add_f32_e32 v144, 0, v145
	v_add_f32_e32 v144, v187, v144
	s_waitcnt lgkmcnt(3)
	v_mfma_f32_32x32x16_bf16 v[80:95], v[64:67], v[112:115], 0
	v_add_f32_e32 v144, v146, v144
	v_add_f32_e32 v144, v188, v144
	v_add_f32_e32 v144, v186, v144
	v_add_f32_e32 v144, v189, v144
	v_add_f32_e32 v144, v147, v144
	v_add_f32_e32 v144, v185, v144
	v_add_f32_e32 v144, v157, v144
	s_waitcnt lgkmcnt(2)
	v_mfma_f32_32x32x16_bf16 v[64:79], v[68:71], v[112:115], 0
	v_add_f32_e32 v144, v181, v144
	v_add_f32_e32 v144, v179, v144
	v_add_f32_e32 v144, v182, v144
	v_exp_f32_e32 v142, v142
	v_add_f32_e32 v144, v154, v144
	v_exp_f32_e32 v143, v143
	v_add_f32_e32 v144, v155, v144
	s_waitcnt lgkmcnt(1)
	v_mfma_f32_32x32x16_bf16 v[80:95], v[194:197], v[108:111], v[80:95]
	v_exp_f32_e32 v140, v140
	v_add_f32_e32 v144, v156, v144
	v_exp_f32_e32 v141, v141
	v_add_f32_e32 v144, v180, v144
	v_exp_f32_e32 v136, v136
	v_add_f32_e32 v144, v142, v144
	v_exp_f32_e32 v137, v137
	s_waitcnt lgkmcnt(0)
	v_mfma_f32_32x32x16_bf16 v[64:79], v[198:201], v[108:111], v[64:79]
	ds_read_b128 v[194:197], v169 offset:49152
	ds_read_b128 v[198:201], v169 offset:57344
	v_add_f32_e32 v144, v143, v144
	v_exp_f32_e32 v132, v132
	v_add_f32_e32 v144, v140, v144
	v_exp_f32_e32 v133, v133
	v_add_f32_e32 v144, v141, v144
	v_exp_f32_e32 v130, v130
	s_waitcnt lgkmcnt(1)
	v_mfma_f32_32x32x16_bf16 v[80:95], v[194:197], v[120:123], v[80:95]
	v_add_f32_e32 v144, v136, v144
	v_exp_f32_e32 v131, v131
	v_add_f32_e32 v144, v137, v144
	v_exp_f32_e32 v138, v138
	v_add_f32_e32 v144, v132, v144
	v_exp_f32_e32 v139, v139
	v_add_f32_e32 v144, v133, v144
	s_waitcnt lgkmcnt(0)
	v_mfma_f32_32x32x16_bf16 v[64:79], v[198:201], v[120:123], v[64:79]
	ds_read_b128 v[194:197], v168 offset:49152
	ds_read_b128 v[198:201], v168 offset:57344
	v_exp_f32_e32 v134, v134
	v_add_f32_e32 v144, v130, v144
	v_exp_f32_e32 v135, v135
	v_add_f32_e32 v144, v131, v144
	v_exp_f32_e32 v128, v128
	v_add_f32_e32 v144, v138, v144
	s_waitcnt lgkmcnt(1)
	v_mfma_f32_32x32x16_bf16 v[80:95], v[194:197], v[124:127], v[80:95]
	v_exp_f32_e32 v129, v129
	v_add_f32_e32 v144, v139, v144
	v_add_f32_e32 v144, v134, v144
	v_add_f32_e32 v144, v135, v144
	v_add_f32_e32 v144, v128, v144
	v_add_f32_e32 v175, v129, v144
	v_mov_b32_e32 v176, v175
	s_waitcnt lgkmcnt(0)
	v_mfma_f32_32x32x16_bf16 v[64:79], v[198:201], v[124:127], v[64:79]
	ds_read_b128 v[194:197], v167 offset:49152
	ds_read_b128 v[198:201], v167 offset:57344
	v_permlane32_swap_b32_e32 v175, v176
	s_waitcnt lgkmcnt(1)
	v_mfma_f32_32x32x16_bf16 v[80:95], v[194:197], v[116:119], v[80:95]
	s_waitcnt lgkmcnt(0)
	v_mfma_f32_32x32x16_bf16 v[64:79], v[198:201], v[116:119], v[64:79]
	ds_read_b128 v[194:197], v166 offset:49152
	ds_read_b128 v[198:201], v166 offset:57344
	s_waitcnt lgkmcnt(1)
	v_mfma_f32_32x32x16_bf16 v[80:95], v[194:197], v[104:107], v[80:95]
	s_waitcnt lgkmcnt(0)
	v_mfma_f32_32x32x16_bf16 v[64:79], v[198:201], v[104:107], v[64:79]
	ds_read_b128 v[194:197], v172 offset:49152
	ds_read_b128 v[198:201], v172 offset:57344
	s_waitcnt lgkmcnt(1)
	v_mfma_f32_32x32x16_bf16 v[80:95], v[194:197], v[100:103], v[80:95]
	s_waitcnt lgkmcnt(0)
	v_mfma_f32_32x32x16_bf16 v[64:79], v[198:201], v[100:103], v[64:79]
	ds_read_b128 v[194:197], v171 offset:49152
	ds_read_b128 v[198:201], v171 offset:57344
	v_cvt_pk_bf16_f32 v144, v145, v187
	v_cvt_pk_bf16_f32 v145, v146, v188
	v_cvt_pk_bf16_f32 v146, v186, v189
	v_cvt_pk_bf16_f32 v147, v147, v185
	v_cvt_pk_bf16_f32 v184, v157, v181
	v_cvt_pk_bf16_f32 v185, v179, v182
	s_waitcnt lgkmcnt(1)
	v_mfma_f32_32x32x16_bf16 v[80:95], v[194:197], v[96:99], v[80:95]
	v_permlane32_swap_b32_e32 v144, v146
	v_cvt_pk_bf16_f32 v186, v154, v155
	v_cvt_pk_bf16_f32 v187, v156, v180
	v_cvt_pk_bf16_f32 v180, v142, v143
	v_cvt_pk_bf16_f32 v181, v140, v141
	v_cvt_pk_bf16_f32 v182, v136, v137
	s_waitcnt lgkmcnt(0)
	v_mfma_f32_32x32x16_bf16 v[64:79], v[198:201], v[96:99], v[64:79]
	v_cvt_pk_bf16_f32 v183, v132, v133
	v_cvt_pk_bf16_f32 v188, v130, v131
	v_cvt_pk_bf16_f32 v189, v138, v139
	v_cvt_pk_bf16_f32 v190, v134, v135
	v_cvt_pk_bf16_f32 v191, v128, v129
	v_permlane32_swap_b32_e32 v145, v147
	v_permlane32_swap_b32_e32 v184, v186
	v_permlane32_swap_b32_e32 v185, v187
	v_permlane32_swap_b32_e32 v180, v182
	v_permlane32_swap_b32_e32 v181, v183
	v_permlane32_swap_b32_e32 v188, v190
	v_permlane32_swap_b32_e32 v189, v191
	v_lshl_add_u64 v[154:155], s[10:11], 0, v[192:193]
	v_add_co_u32_e32 v128, vcc, s0, v154
	v_lshl_add_u64 v[156:157], s[10:11], 0, v[152:153]
	s_nop 0
	v_addc_co_u32_e32 v129, vcc, 0, v155, vcc
	v_add_co_u32_e32 v132, vcc, s0, v156
	s_nop 1
	v_addc_co_u32_e32 v133, vcc, 0, v157, vcc
	v_add_co_u32_e32 v136, vcc, s67, v154
	global_load_dwordx4 v[128:131], v[128:129], off
	s_nop 0
	global_load_dwordx4 v[132:135], v[132:133], off
	v_addc_co_u32_e32 v137, vcc, 0, v155, vcc
	v_add_co_u32_e32 v140, vcc, s67, v156
	s_nop 1
	v_addc_co_u32_e32 v141, vcc, 0, v157, vcc
	global_load_dwordx4 v[136:139], v[136:137], off
	s_nop 0
	global_load_dwordx4 v[140:143], v[140:141], off
	ds_read_b64_tr_b16 v[194:195], v160 offset:0
	ds_read_b64_tr_b16 v[196:197], v160 offset:0x800
	ds_read_b64_tr_b16 v[198:199], v160 offset:0x1000
	ds_read_b64_tr_b16 v[200:201], v160 offset:0x1800
	ds_read_b64_tr_b16 v[202:203], v160 offset:0x2000
	ds_read_b64_tr_b16 v[204:205], v160 offset:0x2800
	ds_read_b64_tr_b16 v[206:207], v160 offset:0x3000
	ds_read_b64_tr_b16 v[208:209], v160 offset:0x3800
	s_waitcnt lgkmcnt(0)
; #define SBAR() __builtin_amdgcn_sched_barrier(0)
; template <int DK>
; __device__ __forceinline__ void partialSM(f32x16& p0, f32x16& p1, float& m_reg, float& mn, float& alpha) {
;   constexpr float SCALE = Cst<DK>::SCALE, C = SCALE * 1.4426950408889634f;
;   float pmax = p0[0];
; #pragma unroll
;   for (int r = 1; r < 16; ++r) pmax = fmaxf(pmax, p0[r]);
; #pragma unroll
;   for (int r = 0; r < 16; ++r) pmax = fmaxf(pmax, p1[r]);
;   { auto rr = __builtin_amdgcn_permlane32_swap(__float_as_uint(pmax), __float_as_uint(pmax), false, false);
;     pmax = fmaxf(__uint_as_float(rr[0]), __uint_as_float(rr[1])); }
;   if (__builtin_expect(__all(pmax - m_reg <= THR / SCALE), 1)) { mn = m_reg; alpha = 1.f; }
;   else { mn = fmaxf(m_reg, pmax); alpha = __builtin_amdgcn_exp2f((m_reg - mn) * C); m_reg = mn; }
;   float mnC = -mn * C;
; #pragma unroll
;   for (int r = 0; r < 16; ++r) p0[r] = fmaf(p0[r], C, mnC);
; #pragma unroll
;   for (int r = 0; r < 16; ++r) p1[r] = fmaf(p1[r], C, mnC);
; #pragma unroll
;   for (int r = 0; r < 16; ++r) p0[r] = __builtin_amdgcn_exp2f(p0[r]);
; }
; template <int D0> __device__ __forceinline__ void pv_one(f32x16& od, int vb, bf16x8 pa0, bf16x8 pa1, bf16x8 pa2, bf16x8 pa3) {
;   const s16x4 l0 = tr_read<v_rd_off(D0, 0, 0)>(vb), h0 = tr_read<v_rd_off(D0, 0, 1)>(vb), l1 = tr_read<v_rd_off(D0, 1, 0)>(vb), h1 = tr_read<v_rd_off(D0, 1, 1)>(vb);
;   const s16x4 l2 = tr_read<v_rd_off(D0, 2, 0)>(vb), h2 = tr_read<v_rd_off(D0, 2, 1)>(vb), l3 = tr_read<v_rd_off(D0, 3, 0)>(vb), h3 = tr_read<v_rd_off(D0, 3, 1)>(vb);
;   asm volatile("s_waitcnt lgkmcnt(0)" ::: "memory"); SBAR();
;     ...
;   od = __builtin_amdgcn_mfma_f32_32x32x16_bf16(pa0, PK(l0, h0), od, 0, 0, 0);
;   od = __builtin_amdgcn_mfma_f32_32x32x16_bf16(pa1, PK(l1, h1), od, 0, 0, 0);
;   od = __builtin_amdgcn_mfma_f32_32x32x16_bf16(pa2, PK(l2, h2), od, 0, 0, 0);
;   od = __builtin_amdgcn_mfma_f32_32x32x16_bf16(pa3, PK(l3, h3), od, 0, 0, 0);
;     ...
; }
; __device__ __forceinline__ void pv_d0(f32x16* o, int vb, bf16x8 pa0, bf16x8 pa1, bf16x8 pa2, bf16x8 pa3) {
;   pv_one<0>(o[0], vb, pa0, pa1, pa2, pa3); pv_one<1>(o[1], vb, pa0, pa1, pa2, pa3); pv_one<2>(o[2], vb, pa0, pa1, pa2, pa3); pv_one<3>(o[3], vb, pa0, pa1, pa2, pa3);
; }
	s_nop 0
	v_mfma_f32_32x32x16_bf16 v[0:15], v[144:147], v[194:197], v[0:15]
	ds_read_b64_tr_b16 v[194:195], v160 offset:0x200
	ds_read_b64_tr_b16 v[196:197], v160 offset:0xa00
	v_max_f32_e32 v248, v81, v81
	v_max_f32_e32 v249, v80, v80
	v_max_f32_e32 v248, v249, v248
	v_max3_f32 v248, v248, v82, v83
	v_max3_f32 v248, v248, v84, v85
	v_mfma_f32_32x32x16_bf16 v[0:15], v[184:187], v[198:201], v[0:15]
	ds_read_b64_tr_b16 v[198:199], v160 offset:0x1200
	ds_read_b64_tr_b16 v[200:201], v160 offset:0x1a00
	v_max3_f32 v248, v248, v86, v87
	v_max3_f32 v248, v248, v88, v89
	v_max3_f32 v248, v248, v90, v91
	v_max3_f32 v248, v248, v92, v93
	v_max3_f32 v248, v248, v94, v95
	v_mfma_f32_32x32x16_bf16 v[0:15], v[180:183], v[202:205], v[0:15]
	ds_read_b64_tr_b16 v[202:203], v160 offset:0x2200
	ds_read_b64_tr_b16 v[204:205], v160 offset:0x2a00
	v_max3_f32 v248, v248, v64, v65
	v_max3_f32 v248, v248, v66, v67
	v_max3_f32 v248, v248, v68, v69
	v_max3_f32 v248, v248, v70, v71
	v_mfma_f32_32x32x16_bf16 v[0:15], v[188:191], v[206:209], v[0:15]
	ds_read_b64_tr_b16 v[206:207], v160 offset:0x3200
	ds_read_b64_tr_b16 v[208:209], v160 offset:0x3a00
	v_max3_f32 v248, v248, v72, v73
	v_max3_f32 v248, v248, v74, v75
	v_max3_f32 v248, v248, v76, v77
	v_max3_f32 v248, v248, v78, v79
	s_waitcnt lgkmcnt(0)
	v_mfma_f32_32x32x16_bf16 v[48:63], v[144:147], v[194:197], v[48:63]
	ds_read_b64_tr_b16 v[194:195], v160 offset:0x400
	ds_read_b64_tr_b16 v[196:197], v160 offset:0xc00
	v_mov_b32_e32 v249, v248
	v_mfma_f32_32x32x16_bf16 v[48:63], v[184:187], v[198:201], v[48:63]
	ds_read_b64_tr_b16 v[198:199], v160 offset:0x1400
	ds_read_b64_tr_b16 v[200:201], v160 offset:0x1c00
	v_permlane32_swap_b32_e32 v248, v249
	v_max_f32_e32 v249, v249, v249
	v_max_f32_e32 v248, v248, v248
	v_max_f32_e32 v248, v248, v249
	v_mfma_f32_32x32x16_bf16 v[48:63], v[180:183], v[202:205], v[48:63]
	ds_read_b64_tr_b16 v[202:203], v160 offset:0x2400
	ds_read_b64_tr_b16 v[204:205], v160 offset:0x2c00
	v_sub_f32_e32 v249, v248, v174
	v_cmp_ge_f32_e32 vcc, s1, v249
	v_max_f32_e32 v249, v174, v174
	v_max_f32_e32 v248, v249, v248
	v_mfma_f32_32x32x16_bf16 v[48:63], v[188:191], v[206:209], v[48:63]
	ds_read_b64_tr_b16 v[206:207], v160 offset:0x3400
	ds_read_b64_tr_b16 v[208:209], v160 offset:0x3c00
	v_sub_f32_e32 v249, v174, v248
	v_mul_f32_e32 v249, 0x3e0293ee, v249
	v_exp_f32_e32 v249, v249
	s_waitcnt lgkmcnt(0)
	v_mfma_f32_32x32x16_bf16 v[32:47], v[144:147], v[194:197], v[32:47]
	ds_read_b64_tr_b16 v[194:195], v160 offset:0x600
	ds_read_b64_tr_b16 v[196:197], v160 offset:0xe00
	s_cmp_eq_u64 vcc, exec
	s_cselect_b64 s[8:9], -1, 0
	v_cndmask_b32_e64 v174, v248, v174, s[8:9]
	v_mul_f32_e32 v250, 0xbe0293ee, v174
	v_mfma_f32_32x32x16_bf16 v[32:47], v[184:187], v[198:201], v[32:47]
	ds_read_b64_tr_b16 v[198:199], v160 offset:0x1600
	ds_read_b64_tr_b16 v[200:201], v160 offset:0x1e00
	v_fmamk_f32 v80, v80, 0x3e0293ee, v250
	v_fmamk_f32 v81, v81, 0x3e0293ee, v250
	v_fmamk_f32 v82, v82, 0x3e0293ee, v250
	v_fmamk_f32 v83, v83, 0x3e0293ee, v250
	v_fmamk_f32 v84, v84, 0x3e0293ee, v250
	v_fmamk_f32 v85, v85, 0x3e0293ee, v250
	v_mfma_f32_32x32x16_bf16 v[32:47], v[180:183], v[202:205], v[32:47]
	ds_read_b64_tr_b16 v[202:203], v160 offset:0x2600
	ds_read_b64_tr_b16 v[204:205], v160 offset:0x2e00
	v_fmamk_f32 v86, v86, 0x3e0293ee, v250
	v_fmamk_f32 v87, v87, 0x3e0293ee, v250
	v_fmamk_f32 v88, v88, 0x3e0293ee, v250
	v_fmamk_f32 v89, v89, 0x3e0293ee, v250
	v_fmamk_f32 v90, v90, 0x3e0293ee, v250
	v_fmamk_f32 v91, v91, 0x3e0293ee, v250
	v_mfma_f32_32x32x16_bf16 v[32:47], v[188:191], v[206:209], v[32:47]
	ds_read_b64_tr_b16 v[206:207], v160 offset:0x3600
	ds_read_b64_tr_b16 v[208:209], v160 offset:0x3e00
	v_fmamk_f32 v92, v92, 0x3e0293ee, v250
	v_fmamk_f32 v93, v93, 0x3e0293ee, v250
	v_fmamk_f32 v94, v94, 0x3e0293ee, v250
	v_fmamk_f32 v95, v95, 0x3e0293ee, v250
	v_fmamk_f32 v214, v64, 0x3e0293ee, v250
	v_fmamk_f32 v215, v65, 0x3e0293ee, v250
	s_waitcnt lgkmcnt(0)
	v_mfma_f32_32x32x16_bf16 v[16:31], v[144:147], v[194:197], v[16:31]
	v_fmamk_f32 v216, v66, 0x3e0293ee, v250
	v_fmamk_f32 v217, v67, 0x3e0293ee, v250
	v_fmamk_f32 v218, v68, 0x3e0293ee, v250
	v_fmamk_f32 v219, v69, 0x3e0293ee, v250
	v_fmamk_f32 v220, v70, 0x3e0293ee, v250
	v_fmamk_f32 v221, v71, 0x3e0293ee, v250
	v_exp_f32_e32 v230, v80
	v_exp_f32_e32 v231, v81
	v_mfma_f32_32x32x16_bf16 v[16:31], v[184:187], v[198:201], v[16:31]
	v_fmamk_f32 v222, v72, 0x3e0293ee, v250
	v_fmamk_f32 v223, v73, 0x3e0293ee, v250
	v_fmamk_f32 v224, v74, 0x3e0293ee, v250
	v_fmamk_f32 v225, v75, 0x3e0293ee, v250
	v_exp_f32_e32 v232, v82
	v_exp_f32_e32 v233, v83
	v_exp_f32_e32 v234, v84
	v_mfma_f32_32x32x16_bf16 v[16:31], v[180:183], v[202:205], v[16:31]
	v_fmamk_f32 v226, v76, 0x3e0293ee, v250
	v_fmamk_f32 v227, v77, 0x3e0293ee, v250
	v_fmamk_f32 v228, v78, 0x3e0293ee, v250
	v_fmamk_f32 v229, v79, 0x3e0293ee, v250
	v_exp_f32_e32 v235, v85
	v_exp_f32_e32 v236, v86
	v_exp_f32_e32 v237, v87
	v_mfma_f32_32x32x16_bf16 v[16:31], v[188:191], v[206:209], v[16:31]
	v_exp_f32_e32 v238, v88
	v_exp_f32_e32 v239, v89
	v_exp_f32_e32 v240, v90
	v_exp_f32_e32 v242, v91
	v_exp_f32_e32 v244, v92
	v_exp_f32_e32 v245, v93
	v_exp_f32_e32 v246, v94
	v_exp_f32_e32 v247, v95
	s_barrier
	s_waitcnt vmcnt(0)
	v_cndmask_b32_e64 v177, v249, 1.0, s[8:9]
	v_cmp_gt_f32_e32 vcc, 1.0, v177
	s_waitcnt vmcnt(3)
	ds_write_b128 v164, v[128:131]
	s_waitcnt vmcnt(2)
	ds_write_b128 v165, v[132:135]
	s_waitcnt vmcnt(1)
	ds_write_b128 v162, v[136:139] offset:32768
	s_waitcnt vmcnt(0)
	ds_write_b128 v163, v[140:143] offset:32768
	s_cbranch_vccz .LBB0_928
; #define SBAR() __builtin_amdgcn_sched_barrier(0)
; #define SWAIT() do { if constexpr (SDEPTH == 2) { if constexpr (DK == 192) asm volatile("s_waitcnt vmcnt(5)" ::: "memory"); else asm volatile("s_waitcnt vmcnt(4)" ::: "memory"); } else asm volatile("s_waitcnt vmcnt(0)" ::: "memory"); } while (0)
; __device__ __forceinline__ void finishSM(f32x16& p0, f32x16& p1, float alpha, float& l_reg, bf16x8& pa0, bf16x8& pa1, bf16x8& pa2, bf16x8& pa3) {
; #pragma unroll
;   for (int r = 0; r < 16; ++r) p1[r] = __builtin_amdgcn_exp2f(p1[r]);
;   float ps = 0;
; #pragma unroll
;   for (int r = 0; r < 16; ++r) ps += p0[r];
; #pragma unroll
;   for (int r = 0; r < 16; ++r) ps += p1[r];
;   { auto rr = __builtin_amdgcn_permlane32_swap(__float_as_uint(ps), __float_as_uint(ps), false, false);
;     ps = __uint_as_float(rr[0]) + __uint_as_float(rr[1]); }
;   l_reg = l_reg * alpha + ps;
;     ...
;   PK4(p0, 0, pa0); PK4(p0, 8, pa1); PK4(p1, 0, pa2); PK4(p1, 8, pa3);
;     ...
; }
; template <int DK, int NPARK>
; __device__ __forceinline__ void qkt(f32x16& p0, f32x16& p1, const char* Ks, const bf16x8* qr, const char* qpark, int r32, int hi) {
;   p0 = f32x16{}; p1 = f32x16{};
; #pragma unroll
;   for (int d0 = 0; d0 < DK / 16; ++d0) { const int cb = (d0 * 16 + hi * 8) * 2;
;     bf16x8 b0 = *reinterpret_cast<const bf16x8*>(Ks + kswz<DK>(r32, cb));
;     bf16x8 b1 = *reinterpret_cast<const bf16x8*>(Ks + kswz<DK>(32 + r32, cb));
;     bf16x8 q;
;     if constexpr (NPARK > 0) { if (d0 >= DK / 16 - NPARK) q = *reinterpret_cast<const bf16x8*>(qpark + (d0 - (DK / 16 - NPARK)) * 1024); else q = qr[d0]; } else q = qr[d0];
;     p0 = __builtin_amdgcn_mfma_f32_32x32x16_bf16(b0, q, p0, 0, 0, 0);
;     p1 = __builtin_amdgcn_mfma_f32_32x32x16_bf16(b1, q, p1, 0, 0, 0); }
; }
; template <int DK, int LDQ, int LDK, int LDV, int LDO, int SDEPTH, int NPARK>
; __device__ __forceinline__ void body(const bf16_t* __restrict__ Qb, const bf16_t* __restrict__ Kh, const bf16_t* __restrict__ Vh, bf16_t* __restrict__ Ob, int seq, char* lds, int tid, int wid) {
;     ...
;     __syncthreads(); SWAIT(); SWRITE(0, SE);
;     RESC(alB); __syncthreads();
;     SBAR(); qkt<DK, NPARK>(pA0, pA1, K_lds, qr, qpark, r32, hi);
;     finishSM(pB0, pB1, alB, l_reg, pa0, pa1, pa2, pa3); SBAR();
	s_and_saveexec_b64 s[12:13], s[6:7]
	ds_write_b32 v151, v177 offset:128
	s_or_b64 exec, exec, s[12:13]
	s_waitcnt lgkmcnt(0)
	v_add_u32_e32 v140, s95, v150
	ds_read_b128 v[128:131], v140 offset:224
	ds_read_b128 v[132:135], v140 offset:192
	ds_read_b128 v[136:139], v140 offset:160
	ds_read_b128 v[140:143], v140 offset:128
	s_waitcnt lgkmcnt(3)
	v_pk_mul_f32 v[12:13], v[12:13], v[128:129]
	s_waitcnt lgkmcnt(2)
	v_pk_mul_f32 v[8:9], v[8:9], v[132:133]
	s_waitcnt lgkmcnt(1)
	v_pk_mul_f32 v[4:5], v[4:5], v[136:137]
	v_pk_mul_f32 v[14:15], v[14:15], v[130:131]
	v_pk_mul_f32 v[10:11], v[10:11], v[134:135]
	v_pk_mul_f32 v[6:7], v[6:7], v[138:139]
	s_waitcnt lgkmcnt(0)
	v_pk_mul_f32 v[2:3], v[2:3], v[142:143]
	v_pk_mul_f32 v[0:1], v[0:1], v[140:141]
	v_pk_mul_f32 v[60:61], v[60:61], v[128:129]
	v_pk_mul_f32 v[56:57], v[56:57], v[132:133]
	v_pk_mul_f32 v[52:53], v[52:53], v[136:137]
	v_pk_mul_f32 v[62:63], v[62:63], v[130:131]
	v_pk_mul_f32 v[58:59], v[58:59], v[134:135]
	v_pk_mul_f32 v[54:55], v[54:55], v[138:139]
	v_pk_mul_f32 v[50:51], v[50:51], v[142:143]
	v_pk_mul_f32 v[48:49], v[48:49], v[140:141]
	v_pk_mul_f32 v[44:45], v[44:45], v[128:129]
	v_pk_mul_f32 v[40:41], v[40:41], v[132:133]
	v_pk_mul_f32 v[36:37], v[36:37], v[136:137]
	v_pk_mul_f32 v[46:47], v[46:47], v[130:131]
	v_pk_mul_f32 v[42:43], v[42:43], v[134:135]
	v_pk_mul_f32 v[38:39], v[38:39], v[138:139]
	v_pk_mul_f32 v[34:35], v[34:35], v[142:143]
	v_pk_mul_f32 v[32:33], v[32:33], v[140:141]
	v_pk_mul_f32 v[28:29], v[28:29], v[128:129]
	v_pk_mul_f32 v[24:25], v[24:25], v[132:133]
	v_pk_mul_f32 v[20:21], v[20:21], v[136:137]
	v_pk_mul_f32 v[30:31], v[30:31], v[130:131]
	v_pk_mul_f32 v[26:27], v[26:27], v[134:135]
	v_pk_mul_f32 v[22:23], v[22:23], v[138:139]
	v_pk_mul_f32 v[18:19], v[18:19], v[142:143]
	v_pk_mul_f32 v[16:17], v[16:17], v[140:141]
.LBB0_928:
	s_waitcnt lgkmcnt(0)
	s_barrier
	ds_read_b128 v[64:67], v161 offset:32768
	ds_read_b128 v[68:71], v161 offset:40960
	ds_read_b128 v[194:197], v170 offset:32768
	ds_read_b128 v[198:201], v170 offset:40960
	v_exp_f32_e32 v203, v229
	v_add_f32_e32 v144, 0, v230
	s_waitcnt lgkmcnt(3)
	v_mfma_f32_32x32x16_bf16 v[80:95], v[64:67], v[112:115], 0
	v_add_f32_e32 v144, v231, v144
	v_add_f32_e32 v144, v232, v144
	v_add_f32_e32 v144, v233, v144
	v_add_f32_e32 v144, v234, v144
	v_add_f32_e32 v144, v235, v144
	v_add_f32_e32 v144, v236, v144
	v_add_f32_e32 v144, v237, v144
	s_waitcnt lgkmcnt(2)
	v_mfma_f32_32x32x16_bf16 v[64:79], v[68:71], v[112:115], 0
	v_add_f32_e32 v144, v238, v144
	v_add_f32_e32 v144, v239, v144
	v_add_f32_e32 v144, v240, v144
	v_add_f32_e32 v144, v242, v144
	v_exp_f32_e32 v191, v214
	v_add_f32_e32 v144, v244, v144
	v_exp_f32_e32 v185, v215
	s_waitcnt lgkmcnt(1)
	v_mfma_f32_32x32x16_bf16 v[80:95], v[194:197], v[108:111], v[80:95]
	v_add_f32_e32 v144, v245, v144
	v_add_f32_e32 v144, v246, v144
	v_add_f32_e32 v144, v247, v144
	v_add_f32_e32 v144, v191, v144
	v_add_f32_e32 v144, v185, v144
	v_exp_f32_e32 v179, v221
	v_exp_f32_e32 v180, v222
	s_waitcnt lgkmcnt(0)
	v_mfma_f32_32x32x16_bf16 v[64:79], v[198:201], v[108:111], v[64:79]
	ds_read_b128 v[194:197], v169 offset:32768
	ds_read_b128 v[198:201], v169 offset:40960
	v_exp_f32_e32 v181, v223
	v_exp_f32_e32 v182, v224
	v_exp_f32_e32 v202, v227
	v_exp_f32_e32 v190, v228
	s_waitcnt lgkmcnt(1)
	v_mfma_f32_32x32x16_bf16 v[80:95], v[194:197], v[120:123], v[80:95]
	s_waitcnt lgkmcnt(0)
	v_mfma_f32_32x32x16_bf16 v[64:79], v[198:201], v[120:123], v[64:79]
	ds_read_b128 v[194:197], v168 offset:32768
	ds_read_b128 v[198:201], v168 offset:40960
	s_waitcnt lgkmcnt(1)
	v_mfma_f32_32x32x16_bf16 v[80:95], v[194:197], v[124:127], v[80:95]
	s_waitcnt lgkmcnt(0)
	v_mfma_f32_32x32x16_bf16 v[64:79], v[198:201], v[124:127], v[64:79]
	ds_read_b128 v[194:197], v167 offset:32768
	ds_read_b128 v[198:201], v167 offset:40960
	s_waitcnt lgkmcnt(1)
	v_mfma_f32_32x32x16_bf16 v[80:95], v[194:197], v[116:119], v[80:95]
	s_waitcnt lgkmcnt(0)
	v_mfma_f32_32x32x16_bf16 v[64:79], v[198:201], v[116:119], v[64:79]
	ds_read_b128 v[194:197], v166 offset:32768
	ds_read_b128 v[198:201], v166 offset:40960
	s_waitcnt lgkmcnt(1)
	v_mfma_f32_32x32x16_bf16 v[80:95], v[194:197], v[104:107], v[80:95]
	s_waitcnt lgkmcnt(0)
	v_mfma_f32_32x32x16_bf16 v[64:79], v[198:201], v[104:107], v[64:79]
	ds_read_b128 v[194:197], v172 offset:32768
	ds_read_b128 v[198:201], v172 offset:40960
	s_waitcnt lgkmcnt(1)
	v_mfma_f32_32x32x16_bf16 v[80:95], v[194:197], v[100:103], v[80:95]
	s_waitcnt lgkmcnt(0)
	v_mfma_f32_32x32x16_bf16 v[64:79], v[198:201], v[100:103], v[64:79]
	ds_read_b128 v[194:197], v171 offset:32768
	ds_read_b128 v[198:201], v171 offset:40960
	s_waitcnt lgkmcnt(1)
	v_mfma_f32_32x32x16_bf16 v[80:95], v[194:197], v[96:99], v[80:95]
	v_exp_f32_e32 v195, v216
	v_exp_f32_e32 v196, v217
	v_exp_f32_e32 v197, v218
	v_add_f32_e32 v144, v195, v144
	v_add_f32_e32 v144, v196, v144
	v_add_f32_e32 v144, v197, v144
	s_waitcnt lgkmcnt(0)
; #define SBAR() __builtin_amdgcn_sched_barrier(0)
; template <int DK>
; __device__ __forceinline__ void partialSM(f32x16& p0, f32x16& p1, float& m_reg, float& mn, float& alpha) {
;   constexpr float SCALE = Cst<DK>::SCALE, C = SCALE * 1.4426950408889634f;
;   float pmax = p0[0];
; #pragma unroll
;   for (int r = 1; r < 16; ++r) pmax = fmaxf(pmax, p0[r]);
; #pragma unroll
;   for (int r = 0; r < 16; ++r) pmax = fmaxf(pmax, p1[r]);
;   { auto rr = __builtin_amdgcn_permlane32_swap(__float_as_uint(pmax), __float_as_uint(pmax), false, false);
;     pmax = fmaxf(__uint_as_float(rr[0]), __uint_as_float(rr[1])); }
;   if (__builtin_expect(__all(pmax - m_reg <= THR / SCALE), 1)) { mn = m_reg; alpha = 1.f; }
;   else { mn = fmaxf(m_reg, pmax); alpha = __builtin_amdgcn_exp2f((m_reg - mn) * C); m_reg = mn; }
;   float mnC = -mn * C;
; #pragma unroll
;   for (int r = 0; r < 16; ++r) p0[r] = fmaf(p0[r], C, mnC);
; #pragma unroll
;   for (int r = 0; r < 16; ++r) p1[r] = fmaf(p1[r], C, mnC);
; #pragma unroll
;   for (int r = 0; r < 16; ++r) p0[r] = __builtin_amdgcn_exp2f(p0[r]);
; }
; __device__ __forceinline__ void finishSM(f32x16& p0, f32x16& p1, float alpha, float& l_reg, bf16x8& pa0, bf16x8& pa1, bf16x8& pa2, bf16x8& pa3) {
; #pragma unroll
;   for (int r = 0; r < 16; ++r) p1[r] = __builtin_amdgcn_exp2f(p1[r]);
;   float ps = 0;
; #pragma unroll
;   for (int r = 0; r < 16; ++r) ps += p0[r];
; #pragma unroll
;   for (int r = 0; r < 16; ++r) ps += p1[r];
;   { auto rr = __builtin_amdgcn_permlane32_swap(__float_as_uint(ps), __float_as_uint(ps), false, false);
;     ps = __uint_as_float(rr[0]) + __uint_as_float(rr[1]); }
;   l_reg = l_reg * alpha + ps;
;     ...
;   PK4(p0, 0, pa0); PK4(p0, 8, pa1); PK4(p1, 0, pa2); PK4(p1, 8, pa3);
;     ...
; }
; template <int DK, int LDQ, int LDK, int LDV, int LDO, int SDEPTH, int NPARK>
; __device__ __forceinline__ void body(const bf16_t* __restrict__ Qb, const bf16_t* __restrict__ Kh, const bf16_t* __restrict__ Vh, bf16_t* __restrict__ Ob, int seq, char* lds, int tid, int wid) {
;     ...
;     finishSM(pB0, pB1, alB, l_reg, pa0, pa1, pa2, pa3); SBAR();
;     if (SDEPTH == 1 || j + 3 < NT) SLOAD(SE, (j + 1 + SDEPTH) * KVBLK); SBAR();
;     pv_d0(o, vb0 + (int)SHM_V, pa0, pa1, pa2, pa3); partialSM<DK>(pA0, pA1, m_reg, mnA, alA);
	v_mfma_f32_32x32x16_bf16 v[64:79], v[198:201], v[96:99], v[64:79]
	v_exp_f32_e32 v198, v219
	v_exp_f32_e32 v199, v220
	v_exp_f32_e32 v200, v225
	v_exp_f32_e32 v201, v226
	v_add_f32_e32 v144, v198, v144
	v_add_f32_e32 v144, v199, v144
	v_add_f32_e32 v144, v179, v144
	v_add_f32_e32 v144, v180, v144
	v_add_f32_e32 v144, v181, v144
	v_add_f32_e32 v144, v182, v144
	v_add_f32_e32 v144, v200, v144
	v_add_f32_e32 v144, v201, v144
	v_add_f32_e32 v144, v202, v144
	v_add_f32_e32 v144, v190, v144
	v_add_f32_e32 v183, v203, v144
	v_mov_b32_e32 v184, v183
	v_cvt_pk_bf16_f32 v144, v230, v231
	v_cvt_pk_bf16_f32 v145, v232, v233
	v_cvt_pk_bf16_f32 v146, v234, v235
	v_cvt_pk_bf16_f32 v147, v236, v237
	s_nop 1
	v_permlane32_swap_b32_e32 v183, v184
	v_permlane32_swap_b32_e32 v144, v146
	v_permlane32_swap_b32_e32 v145, v147
	v_cvt_pk_bf16_f32 v186, v238, v239
	v_cvt_pk_bf16_f32 v187, v240, v242
	v_cvt_pk_bf16_f32 v188, v244, v245
	v_cvt_pk_bf16_f32 v189, v246, v247
	v_cvt_pk_bf16_f32 v194, v191, v185
	v_cvt_pk_bf16_f32 v195, v195, v196
	v_cvt_pk_bf16_f32 v196, v197, v198
	v_cvt_pk_bf16_f32 v197, v199, v179
	v_cvt_pk_bf16_f32 v198, v180, v181
	v_cvt_pk_bf16_f32 v199, v182, v200
	v_cvt_pk_bf16_f32 v200, v201, v202
	v_cvt_pk_bf16_f32 v201, v190, v203
	s_nop 0
	v_permlane32_swap_b32_e32 v186, v188
	v_permlane32_swap_b32_e32 v187, v189
	v_permlane32_swap_b32_e32 v194, v196
	v_permlane32_swap_b32_e32 v195, v197
	v_permlane32_swap_b32_e32 v198, v200
	v_permlane32_swap_b32_e32 v199, v201
	v_add_co_u32_e32 v128, vcc, s61, v154
	s_nop 1
	v_addc_co_u32_e32 v129, vcc, 0, v155, vcc
	v_add_co_u32_e32 v132, vcc, s61, v156
	s_nop 1
	v_addc_co_u32_e32 v133, vcc, 0, v157, vcc
	v_add_co_u32_e32 v136, vcc, s64, v154
	global_load_dwordx4 v[128:131], v[128:129], off
	s_nop 0
	global_load_dwordx4 v[132:135], v[132:133], off
	v_addc_co_u32_e32 v137, vcc, 0, v155, vcc
	v_add_co_u32_e32 v140, vcc, s64, v156
	s_nop 1
	v_addc_co_u32_e32 v141, vcc, 0, v157, vcc
	global_load_dwordx4 v[136:139], v[136:137], off
	s_nop 0
	global_load_dwordx4 v[140:143], v[140:141], off
	ds_read_b64_tr_b16 v[154:155], v159 offset:0
	ds_read_b64_tr_b16 v[156:157], v159 offset:0x800
	ds_read_b64_tr_b16 v[202:203], v159 offset:0x1000
	ds_read_b64_tr_b16 v[204:205], v159 offset:0x1800
	ds_read_b64_tr_b16 v[206:207], v159 offset:0x2000
	ds_read_b64_tr_b16 v[208:209], v159 offset:0x2800
	ds_read_b64_tr_b16 v[210:211], v159 offset:0x3000
	ds_read_b64_tr_b16 v[212:213], v159 offset:0x3800
	s_waitcnt lgkmcnt(0)
	s_nop 0
	v_mfma_f32_32x32x16_bf16 v[0:15], v[144:147], v[154:157], v[0:15]
	ds_read_b64_tr_b16 v[154:155], v159 offset:0x200
	ds_read_b64_tr_b16 v[156:157], v159 offset:0xa00
	v_mfma_f32_32x32x16_bf16 v[0:15], v[186:189], v[202:205], v[0:15]
	ds_read_b64_tr_b16 v[202:203], v159 offset:0x1200
	ds_read_b64_tr_b16 v[204:205], v159 offset:0x1a00
	v_mfma_f32_32x32x16_bf16 v[0:15], v[194:197], v[206:209], v[0:15]
	ds_read_b64_tr_b16 v[206:207], v159 offset:0x2200
	ds_read_b64_tr_b16 v[208:209], v159 offset:0x2a00
	v_mfma_f32_32x32x16_bf16 v[0:15], v[198:201], v[210:213], v[0:15]
	ds_read_b64_tr_b16 v[210:211], v159 offset:0x3200
	ds_read_b64_tr_b16 v[212:213], v159 offset:0x3a00
	s_waitcnt lgkmcnt(0)
	v_mfma_f32_32x32x16_bf16 v[48:63], v[144:147], v[154:157], v[48:63]
	ds_read_b64_tr_b16 v[154:155], v159 offset:0x400
	ds_read_b64_tr_b16 v[156:157], v159 offset:0xc00
	v_mfma_f32_32x32x16_bf16 v[48:63], v[186:189], v[202:205], v[48:63]
	ds_read_b64_tr_b16 v[202:203], v159 offset:0x1400
	ds_read_b64_tr_b16 v[204:205], v159 offset:0x1c00
	v_mfma_f32_32x32x16_bf16 v[48:63], v[194:197], v[206:209], v[48:63]
	ds_read_b64_tr_b16 v[206:207], v159 offset:0x2400
	ds_read_b64_tr_b16 v[208:209], v159 offset:0x2c00
	v_mfma_f32_32x32x16_bf16 v[48:63], v[198:201], v[210:213], v[48:63]
	ds_read_b64_tr_b16 v[210:211], v159 offset:0x3400
	ds_read_b64_tr_b16 v[212:213], v159 offset:0x3c00
	s_waitcnt lgkmcnt(0)
	v_mfma_f32_32x32x16_bf16 v[32:47], v[144:147], v[154:157], v[32:47]
	ds_read_b64_tr_b16 v[154:155], v159 offset:0x600
	ds_read_b64_tr_b16 v[156:157], v159 offset:0xe00
	v_mfma_f32_32x32x16_bf16 v[32:47], v[186:189], v[202:205], v[32:47]
	ds_read_b64_tr_b16 v[202:203], v159 offset:0x1600
	ds_read_b64_tr_b16 v[204:205], v159 offset:0x1e00
	v_mfma_f32_32x32x16_bf16 v[32:47], v[194:197], v[206:209], v[32:47]
	ds_read_b64_tr_b16 v[206:207], v159 offset:0x2600
	ds_read_b64_tr_b16 v[208:209], v159 offset:0x2e00
	v_mfma_f32_32x32x16_bf16 v[32:47], v[198:201], v[210:213], v[32:47]
	ds_read_b64_tr_b16 v[210:211], v159 offset:0x3600
	ds_read_b64_tr_b16 v[212:213], v159 offset:0x3e00
	s_waitcnt lgkmcnt(0)
	v_mfma_f32_32x32x16_bf16 v[16:31], v[144:147], v[154:157], v[16:31]
	v_max_f32_e32 v144, v81, v81
	v_max_f32_e32 v145, v80, v80
	v_max_f32_e32 v144, v145, v144
	v_max3_f32 v144, v144, v82, v83
	v_max3_f32 v144, v144, v84, v85
	v_max3_f32 v144, v144, v86, v87
	v_max3_f32 v144, v144, v88, v89
	v_max3_f32 v144, v144, v90, v91
	v_max3_f32 v144, v144, v92, v93
	v_mfma_f32_32x32x16_bf16 v[16:31], v[186:189], v[202:205], v[16:31]
	v_max3_f32 v144, v144, v94, v95
	v_max3_f32 v144, v144, v64, v65
	v_max3_f32 v144, v144, v66, v67
	v_max3_f32 v144, v144, v68, v69
	v_max3_f32 v144, v144, v70, v71
	v_max3_f32 v144, v144, v72, v73
	v_max3_f32 v144, v144, v74, v75
	v_max3_f32 v144, v144, v76, v77
	v_mfma_f32_32x32x16_bf16 v[16:31], v[194:197], v[206:209], v[16:31]
	v_max3_f32 v144, v144, v78, v79
	v_mov_b32_e32 v145, v144
	s_nop 1
	v_permlane32_swap_b32_e32 v144, v145
	v_max_f32_e32 v145, v145, v145
	v_max_f32_e32 v144, v144, v144
	v_max_f32_e32 v144, v144, v145
	v_sub_f32_e32 v145, v144, v174
	v_cmp_ge_f32_e32 vcc, s1, v145
	v_max_f32_e32 v145, v174, v174
	v_max_f32_e32 v145, v145, v144
	v_mfma_f32_32x32x16_bf16 v[16:31], v[198:201], v[210:213], v[16:31]
	v_sub_f32_e32 v144, v174, v145
	v_mul_f32_e32 v144, 0x3e0293ee, v144
	v_exp_f32_e32 v144, v144
	s_cmp_eq_u64 vcc, exec
	s_cselect_b64 s[8:9], -1, 0
	s_barrier
; #define SWAIT() do { if constexpr (SDEPTH == 2) { if constexpr (DK == 192) asm volatile("s_waitcnt vmcnt(5)" ::: "memory"); else asm volatile("s_waitcnt vmcnt(4)" ::: "memory"); } else asm volatile("s_waitcnt vmcnt(0)" ::: "memory"); } while (0)
; #define RESC(a) do { if (__any((a) < 1.f)) { if (hi == 0) al_l[r32] = (a); asm volatile("s_waitcnt lgkmcnt(0)" ::: "memory"); \
;     _Pragma("unroll") for (int d = 0; d < 4; ++d) _Pragma("unroll") for (int r = 0; r < 16; ++r) o[d][r] *= al_l[crow(r, hi)]; } } while (0)
; template <int DK, int LDQ, int LDK, int LDV, int LDO, int SDEPTH, int NPARK>
; __device__ __forceinline__ void body(const bf16_t* __restrict__ Qb, const bf16_t* __restrict__ Kh, const bf16_t* __restrict__ Vh, bf16_t* __restrict__ Ob, int seq, char* lds, int tid, int wid) {
;     ...
;     __syncthreads(); SWAIT(); SWRITE(1, SO);
;     RESC(alA); __syncthreads();
	s_waitcnt vmcnt(0)
	v_cndmask_b32_e64 v144, v144, 1.0, s[8:9]
	v_cmp_gt_f32_e32 vcc, 1.0, v144
	s_waitcnt vmcnt(3)
	ds_write_b128 v164, v[128:131] offset:16384
	s_waitcnt vmcnt(2)
	ds_write_b128 v165, v[132:135] offset:16384
	s_waitcnt vmcnt(1)
	ds_write_b128 v162, v[136:139] offset:49152
	s_waitcnt vmcnt(0)
	ds_write_b128 v163, v[140:143] offset:49152
	s_cbranch_vccz .LBB0_932
	s_and_saveexec_b64 s[12:13], s[6:7]
	ds_write_b32 v151, v144 offset:128
	s_or_b64 exec, exec, s[12:13]
	s_waitcnt lgkmcnt(0)
	v_add_u32_e32 v140, s95, v150
	ds_read_b128 v[128:131], v140 offset:224
	ds_read_b128 v[132:135], v140 offset:192
	ds_read_b128 v[136:139], v140 offset:160
	ds_read_b128 v[140:143], v140 offset:128
	s_waitcnt lgkmcnt(3)
	v_pk_mul_f32 v[12:13], v[12:13], v[128:129]
	s_waitcnt lgkmcnt(2)
	v_pk_mul_f32 v[8:9], v[8:9], v[132:133]
	s_waitcnt lgkmcnt(1)
	v_pk_mul_f32 v[4:5], v[4:5], v[136:137]
	v_pk_mul_f32 v[14:15], v[14:15], v[130:131]
	v_pk_mul_f32 v[10:11], v[10:11], v[134:135]
	v_pk_mul_f32 v[6:7], v[6:7], v[138:139]
	s_waitcnt lgkmcnt(0)
	v_pk_mul_f32 v[2:3], v[2:3], v[142:143]
	v_pk_mul_f32 v[0:1], v[0:1], v[140:141]
	v_pk_mul_f32 v[60:61], v[60:61], v[128:129]
	v_pk_mul_f32 v[56:57], v[56:57], v[132:133]
	v_pk_mul_f32 v[52:53], v[52:53], v[136:137]
	v_pk_mul_f32 v[62:63], v[62:63], v[130:131]
	v_pk_mul_f32 v[58:59], v[58:59], v[134:135]
	v_pk_mul_f32 v[54:55], v[54:55], v[138:139]
	v_pk_mul_f32 v[50:51], v[50:51], v[142:143]
	v_pk_mul_f32 v[48:49], v[48:49], v[140:141]
	v_pk_mul_f32 v[44:45], v[44:45], v[128:129]
	v_pk_mul_f32 v[40:41], v[40:41], v[132:133]
	v_pk_mul_f32 v[36:37], v[36:37], v[136:137]
	v_pk_mul_f32 v[46:47], v[46:47], v[130:131]
	v_pk_mul_f32 v[42:43], v[42:43], v[134:135]
	v_pk_mul_f32 v[38:39], v[38:39], v[138:139]
	v_pk_mul_f32 v[34:35], v[34:35], v[142:143]
	v_pk_mul_f32 v[32:33], v[32:33], v[140:141]
	v_pk_mul_f32 v[28:29], v[28:29], v[128:129]
	v_pk_mul_f32 v[24:25], v[24:25], v[132:133]
	v_pk_mul_f32 v[20:21], v[20:21], v[136:137]
	v_pk_mul_f32 v[30:31], v[30:31], v[130:131]
	v_pk_mul_f32 v[26:27], v[26:27], v[134:135]
	v_pk_mul_f32 v[22:23], v[22:23], v[138:139]
	v_pk_mul_f32 v[18:19], v[18:19], v[142:143]
	v_pk_mul_f32 v[16:17], v[16:17], v[140:141]
